# RWKV R1 unit (both copies): the five bf16 operand loads issued with the decay loads at the unit head, ahead of the cumsum/barrier section (prologue de-serialisation)
# speedup vs baseline: 1.0022x; 1.0022x over previous
; #define GAS __attribute__((address_space(1)))
; DI unsigned char* lw(unsigned char* p) { unsigned long long w = (unsigned long long)p; asm volatile("" : "+s"(w)); return (unsigned char*)w; }
; #define LD8(dst, OFF) { unpack8(*(const GAS u32x4*)((const bf16*)(ws + (OFF)) + go), dst); }
; DI void u_rwkv_r1(Frame& F, int c, int h) {
;     ...
;     const int t = tid >> 3, j0 = (tid & 7) * 8;
;     const size_t go = gb + (size_t)t * 512 + j0;
;     float lw[8];
;     { const f32x4 x0 = *(const GAS f32x4*)((const float*)(ws + WS_DEC) + go), x1 = *(const GAS f32x4*)((const float*)(ws + WS_DEC) + go + 4);
; #pragma unroll
;       for (int i = 0; i < 4; ++i) { lw[i] = x0[i]; lw[4 + i] = x1[i]; }
; #pragma unroll
;       for (int i = 0; i < 8; ++i) CUM[t * 68 + j0 + i] = lw[i]; }
;     ...
;         LD8(av, WS_KKN) LD8(bv, WS_BB) LD8(kv, WS_KP) LD8(rv, WS_R32) LD8(vv, WS_VV)
.LBB0_1073:
	s_lshl_b32 s9, s8, 3
	v_mov_b32_e32 v39, v38
	s_and_b32 s18, s9, 0xffffffc0
	s_ashr_i32 s19, s18, 31
	s_lshl_b32 s9, s8, 6
	v_ashrrev_i32_e32 v36, 3, v39
	s_lshl_b64 s[18:19], s[18:19], 9
	s_and_b32 s9, s9, 0x1c0
	v_ashrrev_i32_e32 v37, 31, v36
	s_or_b32 s18, s18, s9
	v_lshlrev_b32_e32 v12, 3, v39
	v_lshlrev_b64 v[2:3], 9, v[36:37]
	v_and_b32_e32 v18, 56, v12
	v_lshl_add_u64 v[10:11], s[18:19], 0, v[2:3]
	v_or_b32_e32 v10, v10, v18
	v_lshl_add_u64 v[2:3], v[10:11], 2, s[16:17]
	global_load_dwordx4 v[6:9], v[2:3], off
	s_nop 0
	global_load_dwordx4 v[2:5], v[2:3], off offset:16
	v_lshlrev_b64 v[54:55], 1, v[10:11]
	v_lshl_add_u64 v[56:57], s[48:49], 0, v[54:55]
	global_load_dwordx4 v[32:35], v[56:57], off
	v_lshl_add_u64 v[56:57], s[26:27], 0, v[54:55]
	global_load_dwordx4 v[40:43], v[56:57], off
	v_lshl_add_u64 v[56:57], s[42:43], 0, v[54:55]
	global_load_dwordx4 v[44:47], v[56:57], off
	v_lshl_add_u64 v[56:57], s[44:45], 0, v[54:55]
	global_load_dwordx4 v[48:51], v[56:57], off
	v_lshl_add_u64 v[56:57], s[46:47], 0, v[54:55]
	global_load_dwordx4 v[66:69], v[56:57], off
	v_mul_lo_u32 v13, v36, s94
	v_lshlrev_b32_e32 v14, 2, v18
	v_add3_u32 v13, s20, v13, v14
	v_cmp_gt_i32_e32 vcc, 64, v39
	s_waitcnt vmcnt(5)
	ds_write2_b32 v13, v6, v7 offset1:1
	ds_write2_b32 v13, v8, v9 offset0:2 offset1:3
	ds_write2_b32 v13, v2, v3 offset0:4 offset1:5
	ds_write2_b32 v13, v4, v5 offset0:6 offset1:7
	s_waitcnt lgkmcnt(0)
	s_barrier
	s_and_saveexec_b64 s[18:19], vcc
	s_cbranch_execz .LBB0_1076
	v_lshl_add_u32 v14, v39, 2, s20
	v_mov_b32_e32 v15, 0
	s_mov_b32 s9, 0

; DI float fexp_(float x) { return __builtin_amdgcn_exp2f(x * 1.4426950408889634f); }
; DI unsigned char* lw(unsigned char* p) { unsigned long long w = (unsigned long long)p; asm volatile("" : "+s"(w)); return (unsigned char*)w; }
; #define LD8(dst, OFF) { unpack8(*(const GAS u32x4*)((const bf16*)(ws + (OFF)) + go), dst); }
; DI void u_rwkv_r1(Frame& F, int c, int h) {
;     ...
;         float cum[8], cT[8];
; #pragma unroll
;         for (int i = 0; i < 8; ++i) { cum[i] = CUM[t * 68 + j0 + i]; cT[i] = CUM[63 * 68 + j0 + i]; }
;         if (t == 0) {
; #pragma unroll
;             for (int i = 0; i < 8; ++i) PT[j0 + i] = fexp_(cT[i]); }
;         float av[8], bv[8], kv[8], rv[8], vv[8];
;     ...
;         LD8(av, WS_KKN) LD8(bv, WS_BB) LD8(kv, WS_KP) LD8(rv, WS_R32) LD8(vv, WS_VV)
;     ...
;         float at[8], bh[8], kh[8], rt[8], bj[8], kj[8];
; #pragma unroll
;         for (int i = 0; i < 8; ++i) { const float pprev = fexp_(cum[i] - lw[i]), pinv = fexp_(-cum[i]), pt = fexp_(cum[i]), pend = fexp_(cT[i] - cum[i]);
;             at[i] = -av[i] * pprev; bh[i] = bv[i] * pinv; kh[i] = kv[i] * pinv; rt[i] = rv[i] * pt; bj[i] = bv[i] * pend; kj[i] = kv[i] * pend; }
.LBB0_1076:
	s_or_b64 exec, exec, s[18:19]
	v_lshl_add_u32 v16, v18, 2, s20
	v_add_u32_e32 v17, 0x42f0, v16
	v_add_u32_e32 v22, 0x42f8, v16
	v_add_u32_e32 v23, 0x4300, v16
	s_waitcnt lgkmcnt(0)
	s_barrier
	ds_read2_b32 v[28:29], v13 offset1:1
	ds_read2_b32 v[24:25], v13 offset0:2 offset1:3
	ds_read2_b32 v[20:21], v13 offset0:4 offset1:5
	ds_read2_b32 v[14:15], v13 offset0:6 offset1:7
	v_add_u32_e32 v13, 0x4308, v16
	ds_read2_b32 v[30:31], v17 offset1:1
	ds_read2_b32 v[26:27], v22 offset1:1
	ds_read2_b32 v[22:23], v23 offset1:1
	ds_read2_b32 v[16:17], v13 offset1:1
	v_cmp_gt_u32_e32 vcc, 8, v39
	s_and_saveexec_b64 s[18:19], vcc
	s_cbranch_execz .LBB0_1078
	s_waitcnt lgkmcnt(3)
	v_mul_f32_e32 v52, 0x3fb8aa3b, v30
	v_mul_f32_e32 v53, 0x3fb8aa3b, v31
	v_exp_f32_e32 v52, v52
	v_exp_f32_e32 v53, v53
	v_lshl_add_u32 v12, v12, 2, s20
	v_add_u32_e32 v13, 0x4400, v12
	ds_write2_b32 v13, v52, v53 offset1:1
	s_waitcnt lgkmcnt(3)
	v_mul_f32_e32 v13, 0x3fb8aa3b, v26
	v_mul_f32_e32 v53, 0x3fb8aa3b, v27
	v_exp_f32_e32 v13, v13
	v_exp_f32_e32 v53, v53
	v_add_u32_e32 v52, 0x4408, v12
	ds_write2_b32 v52, v13, v53 offset1:1
	s_waitcnt lgkmcnt(3)
	v_mul_f32_e32 v13, 0x3fb8aa3b, v22
	v_mul_f32_e32 v53, 0x3fb8aa3b, v23
	v_exp_f32_e32 v13, v13
	v_exp_f32_e32 v53, v53
	v_add_u32_e32 v52, 0x4410, v12
	v_add_u32_e32 v12, 0x4418, v12
	ds_write2_b32 v52, v13, v53 offset1:1
	s_waitcnt lgkmcnt(3)
	v_mul_f32_e32 v13, 0x3fb8aa3b, v16
	v_mul_f32_e32 v52, 0x3fb8aa3b, v17
	v_exp_f32_e32 v13, v13
	v_exp_f32_e32 v52, v52
	ds_write2_b32 v12, v13, v52 offset1:1
.LBB0_1078:
	s_or_b64 exec, exec, s[18:19]
	s_waitcnt lgkmcnt(6)
	v_mul_f32_e32 v55, 0x3fb8aa3b, v24
	v_mul_f32_e32 v60, 0x3fb8aa3b, v25
	v_sub_f32_e32 v6, v28, v6
	v_mul_f32_e32 v37, 0xbfb8aa3b, v28
	v_mul_f32_e32 v52, 0x3fb8aa3b, v28
	s_waitcnt lgkmcnt(3)
	v_sub_f32_e32 v28, v30, v28
	s_waitcnt lgkmcnt(2)
	v_sub_f32_e32 v56, v26, v24
	v_sub_f32_e32 v61, v27, v25
	v_exp_f32_e32 v26, v55
	v_exp_f32_e32 v27, v60
	v_sub_f32_e32 v7, v29, v7
	v_mul_f32_e32 v30, 0xbfb8aa3b, v29
	v_mul_f32_e32 v53, 0x3fb8aa3b, v29
	v_sub_f32_e32 v29, v31, v29
	v_sub_f32_e32 v31, v24, v8
	v_mul_f32_e32 v54, 0xbfb8aa3b, v24
	v_sub_f32_e32 v57, v25, v9
	v_mul_f32_e32 v62, 0x3fb8aa3b, v6
	v_exp_f32_e32 v6, v37
	v_mul_f32_e32 v37, 0x3fb8aa3b, v28
	v_mul_f32_e32 v58, 0xbfb8aa3b, v25
	v_exp_f32_e32 v8, v52
	v_mul_f32_e32 v52, 0x3fb8aa3b, v7
	v_exp_f32_e32 v7, v30
	v_mul_f32_e32 v30, 0x3fb8aa3b, v29
	v_mul_f32_e32 v31, 0x3fb8aa3b, v31
	v_exp_f32_e32 v24, v54
	v_mul_f32_e32 v54, 0x3fb8aa3b, v57
	v_mul_f32_e32 v55, 0x3fb8aa3b, v61
	v_exp_f32_e32 v37, v37
	v_exp_f32_e32 v9, v53
	v_mul_f32_e32 v53, 0x3fb8aa3b, v56
	v_exp_f32_e32 v25, v58
	v_exp_f32_e32 v56, v30
	v_exp_f32_e32 v30, v31
	v_exp_f32_e32 v31, v54
	v_exp_f32_e32 v58, v55
	v_sub_f32_e32 v2, v20, v2
	v_exp_f32_e32 v29, v52
	v_exp_f32_e32 v28, v62
	v_exp_f32_e32 v57, v53
	v_sub_f32_e32 v3, v21, v3
	v_mul_f32_e32 v2, 0x3fb8aa3b, v2
	v_mul_f32_e32 v3, 0x3fb8aa3b, v3
	v_exp_f32_e32 v2, v2
	v_exp_f32_e32 v3, v3
	v_and_b32_e32 v59, 15, v39
	s_mov_b64 s[18:19], -1
	s_waitcnt vmcnt(4)
	v_lshlrev_b32_e32 v64, 16, v34
	v_and_b32_e32 v65, 0xffff0000, v34
	v_lshlrev_b32_e32 v60, 16, v32
	v_and_b32_e32 v61, 0xffff0000, v32
	s_waitcnt vmcnt(2)
	v_lshlrev_b32_e32 v34, 16, v44
	v_lshlrev_b32_e32 v62, 16, v33
	v_and_b32_e32 v63, 0xffff0000, v33
	s_waitcnt vmcnt(1)
	v_lshlrev_b32_e32 v52, 16, v48
	v_lshlrev_b32_e32 v32, 16, v40
	s_waitcnt vmcnt(0)
	v_mov_b32_e32 v10, v66
	v_mov_b32_e32 v11, v67
	v_mov_b32_e32 v12, v68
	v_mov_b32_e32 v13, v69
	v_lshlrev_b32_e32 v54, 16, v10
	v_and_b32_e32 v55, 0xffff0000, v10
	v_lshlrev_b32_e32 v10, 16, v11
	v_and_b32_e32 v11, 0xffff0000, v11
	v_pk_mul_f32 v[10:11], v[26:27], v[10:11]
	v_mul_f32_e32 v26, 0xbfb8aa3b, v20
	v_mul_f32_e32 v27, 0x3fb8aa3b, v20
	s_waitcnt lgkmcnt(1)
	v_sub_f32_e32 v20, v22, v20
	v_mul_f32_e32 v20, 0x3fb8aa3b, v20
	v_and_b32_e32 v33, 0xffff0000, v40
	v_lshlrev_b32_e32 v40, 16, v41
	v_and_b32_e32 v41, 0xffff0000, v41
	v_mul_f32_e32 v68, v37, v34
	v_mul_f32_e32 v69, v37, v52
	v_exp_f32_e32 v37, v20
	v_mul_f32_e32 v20, 0xbfb8aa3b, v21
	v_pk_mul_f32 v[30:31], v[30:31], v[40:41] neg_lo:[0,1] neg_hi:[0,1]
	v_exp_f32_e32 v40, v27
	v_exp_f32_e32 v27, v20
	v_mul_f32_e32 v20, 0x3fb8aa3b, v21
	v_exp_f32_e32 v41, v20
	v_sub_f32_e32 v20, v23, v21
	v_lshlrev_b32_e32 v66, 16, v35
	v_and_b32_e32 v67, 0xffff0000, v35
	v_and_b32_e32 v35, 0xffff0000, v44
	v_and_b32_e32 v53, 0xffff0000, v48
	v_lshlrev_b32_e32 v44, 16, v45
	v_and_b32_e32 v45, 0xffff0000, v45
	v_lshlrev_b32_e32 v48, 16, v49
	v_and_b32_e32 v49, 0xffff0000, v49
	v_mul_f32_e32 v20, 0x3fb8aa3b, v20
	v_pk_mul_f32 v[28:29], v[28:29], v[32:33] neg_lo:[0,1] neg_hi:[0,1]
	v_pk_mul_f32 v[32:33], v[6:7], v[34:35]
	v_pk_mul_f32 v[6:7], v[6:7], v[52:53]
	v_pk_mul_f32 v[8:9], v[8:9], v[54:55]
	v_mul_f32_e32 v52, v56, v35
	v_mul_f32_e32 v53, v56, v53
	v_mul_f32_e32 v54, v57, v44
	v_mul_f32_e32 v55, v57, v48
	v_mul_f32_e32 v56, v58, v45
	v_mul_f32_e32 v57, v58, v49
	v_exp_f32_e32 v26, v26
	v_exp_f32_e32 v58, v20
	v_lshlrev_b32_e32 v20, 16, v42
	v_and_b32_e32 v21, 0xffff0000, v42
	v_pk_mul_f32 v[20:21], v[2:3], v[20:21] neg_lo:[0,1] neg_hi:[0,1]
	v_lshlrev_b32_e32 v2, 16, v46
	v_and_b32_e32 v3, 0xffff0000, v46
	v_pk_mul_f32 v[22:23], v[26:27], v[2:3]
	v_mul_f32_e32 v70, v58, v3
	v_mul_f32_e32 v3, 0xbfb8aa3b, v14
	v_pk_mul_f32 v[34:35], v[24:25], v[44:45]
	v_pk_mul_f32 v[24:25], v[24:25], v[48:49]
	v_mul_f32_e32 v46, v37, v2
	v_lshlrev_b32_e32 v48, 16, v12
	v_and_b32_e32 v49, 0xffff0000, v12
	v_sub_f32_e32 v2, v14, v4
	v_exp_f32_e32 v4, v3
	v_mul_f32_e32 v3, 0x3fb8aa3b, v14
	v_pk_mul_f32 v[48:49], v[40:41], v[48:49]
	v_exp_f32_e32 v40, v3
	s_waitcnt lgkmcnt(0)
; #define LAS __attribute__((address_space(3)))
; DI unsigned f2bf(float f) { const __bf16 b = (__bf16)f; return (unsigned)__builtin_bit_cast(unsigned short, b); }
; DI float fexp_(float x) { return __builtin_amdgcn_exp2f(x * 1.4426950408889634f); }
; DI unsigned char* lw(unsigned char* p) { unsigned long long w = (unsigned long long)p; asm volatile("" : "+s"(w)); return (unsigned char*)w; }
; #define MFMA16(a, b, c) __builtin_amdgcn_mfma_f32_16x16x32_bf16((a), (b), (c), 0, 0, 0)
; #define ST8(M, v) { u32x4 o; o.x = pk2(v[0], v[1]); o.y = pk2(v[2], v[3]); o.z = pk2(v[4], v[5]); o.w = pk2(v[6], v[7]); *(LAS u32x4*)(M + t * 72 + j0) = o; }
; DI void u_rwkv_r1(Frame& F, int c, int h) {
;     ...
;         float at[8], bh[8], kh[8], rt[8], bj[8], kj[8];
; #pragma unroll
;         for (int i = 0; i < 8; ++i) { const float pprev = fexp_(cum[i] - lw[i]), pinv = fexp_(-cum[i]), pt = fexp_(cum[i]), pend = fexp_(cT[i] - cum[i]);
;             at[i] = -av[i] * pprev; bh[i] = bv[i] * pinv; kh[i] = kv[i] * pinv; rt[i] = rv[i] * pt; bj[i] = bv[i] * pend; kj[i] = kv[i] * pend; }
;     ...
;         ST8(AT, at) ST8(BH, bh) ST8(KH, kh) ST8(RT, rt)
;     ...
; #pragma unroll
;         for (int i = 0; i < 8; ++i) { const int o = (j0 + i) * 72 + t; AJ[o] = (bf16)f2bf(at[i]); BJ[o] = (bf16)f2bf(bj[i]); KJ[o] = (bf16)f2bf(kj[i]); VJ[o] = (bf16)f2bf(vv[i]); }
;     }
;     __syncthreads();
;     {
;         const int q = w >> 1; const LAS bf16* Am = (q == 0) ? BH : (q == 1) ? KH : RT; const LAS bf16* Bm = (q < 2) ? AT : (q == 2) ? BH : KH;
; #pragma unroll
;         for (int bi = 0; bi < 2; ++bi) { const int bm = 2 * (w & 1) + bi; const bf16x8 a0 = ldfrag(Am, 72, 16 * bm, 0, lane), a1 = ldfrag(Am, 72, 16 * bm, 32, lane);
; #pragma unroll
;             for (int bn = 0; bn < 4; ++bn) { f32x4 acc = (f32x4){0.f, 0.f, 0.f, 0.f};
;                 acc = MFMA16(a0, ldfrag(Bm, 72, 16 * bn, 0, lane), acc); acc = MFMA16(a1, ldfrag(Bm, 72, 16 * bn, 32, lane), acc);
; #pragma unroll
;                 for (int r = 0; r < 4; ++r) { const int row = 16 * bm + 4 * g4 + r, col = 16 * bn + lc; const bool keep = (q < 2) ? (row < col) : (col <= row); const float v = keep ? acc[r] : 0.f;
;                     if (q == 0) CUM[row * 68 + col] = v; else { LAS bf16* O = (q == 1) ? MAK : (q == 2) ? MRBT : MRKT; O[row * 72 + col] = (bf16)f2bf(v); } } } }
	v_sub_f32_e32 v3, v16, v14
	v_mul_f32_e32 v3, 0x3fb8aa3b, v3
	v_exp_f32_e32 v12, v3
	v_sub_f32_e32 v3, v15, v5
	v_mul_f32_e32 v2, 0x3fb8aa3b, v2
	v_mul_f32_e32 v3, 0x3fb8aa3b, v3
	v_mul_f32_e32 v14, 0x3fb8aa3b, v15
	v_exp_f32_e32 v2, v2
	v_exp_f32_e32 v3, v3
	v_mul_f32_e32 v5, 0xbfb8aa3b, v15
	v_exp_f32_e32 v41, v14
	v_sub_f32_e32 v14, v17, v15
	v_lshlrev_b32_e32 v44, 16, v50
	v_exp_f32_e32 v5, v5
	v_mul_f32_e32 v14, 0x3fb8aa3b, v14
	v_and_b32_e32 v45, 0xffff0000, v50
	v_mul_f32_e32 v50, v37, v44
	v_exp_f32_e32 v37, v14
	v_lshlrev_b32_e32 v14, 16, v43
	v_and_b32_e32 v15, 0xffff0000, v43
	v_pk_mul_f32 v[14:15], v[2:3], v[14:15] neg_lo:[0,1] neg_hi:[0,1]
	v_lshlrev_b32_e32 v2, 16, v47
	v_and_b32_e32 v3, 0xffff0000, v47
	v_lshlrev_b32_e32 v42, 16, v51
	v_and_b32_e32 v43, 0xffff0000, v51
	v_pk_mul_f32 v[26:27], v[26:27], v[44:45]
	v_mul_f32_e32 v58, v58, v45
	v_pk_mul_f32 v[16:17], v[4:5], v[2:3]
	v_pk_mul_f32 v[44:45], v[4:5], v[42:43]
	v_lshlrev_b32_e32 v4, 16, v13
	v_and_b32_e32 v5, 0xffff0000, v13
	v_mul_f32_e32 v47, v12, v2
	v_mul_f32_e32 v51, v12, v42
	v_pk_mul_f32 v[12:13], v[40:41], v[4:5]
	v_mul_f32_e32 v41, v37, v3
	v_mul_f32_e32 v43, v37, v43
	v_mul_lo_u32 v37, v36, s95
	v_lshlrev_b32_e32 v37, 1, v37
	v_lshlrev_b32_e32 v40, 1, v18
	v_cvt_pk_bf16_f32 v2, v28, v29
	v_cvt_pk_bf16_f32 v3, v30, v31
	v_cvt_pk_bf16_f32 v4, v20, v21
	v_cvt_pk_bf16_f32 v5, v14, v15
	v_add3_u32 v42, s20, v37, v40
	ds_write_b128 v42, v[2:5] offset:17664
	v_cvt_pk_bf16_f32 v2, v32, v33
	v_cvt_pk_bf16_f32 v3, v34, v35
	v_cvt_pk_bf16_f32 v4, v22, v23
	v_cvt_pk_bf16_f32 v5, v16, v17
	ds_write_b128 v42, v[2:5] offset:26880
	v_cvt_pk_bf16_f32 v2, v6, v7
	v_cvt_pk_bf16_f32 v3, v24, v25
	v_cvt_pk_bf16_f32 v4, v26, v27
	v_cvt_pk_bf16_f32 v5, v44, v45
	ds_write_b128 v42, v[2:5] offset:36096
	v_cvt_pk_bf16_f32 v2, v8, v9
	v_cvt_pk_bf16_f32 v3, v10, v11
	v_cvt_pk_bf16_f32 v4, v48, v49
	v_cvt_pk_bf16_f32 v5, v12, v13
	ds_write_b128 v42, v[2:5] offset:45312
	v_mul_u32_u24_e32 v2, 0x48, v18
	v_add_lshl_u32 v2, v2, v36, 1
	v_cvt_pk_bf16_f32 v3, v28, s0
	v_add_u32_e32 v4, s20, v2
	ds_write_b16 v4, v3 offset:54528
	v_cvt_pk_bf16_f32 v3, v68, s0
	ds_write_b16 v4, v3 offset:63744
	v_cvt_pk_bf16_f32 v3, v69, s0
	v_add_u32_e32 v5, s54, v2
	ds_write_b16 v5, v3
	v_cvt_pk_bf16_f32 v3, v60, s0
	v_add_u32_e32 v2, s24, v2
	ds_write_b16 v2, v3
	v_cvt_pk_bf16_f32 v3, v29, s0
	ds_write_b16 v4, v3 offset:54672
	v_cvt_pk_bf16_f32 v3, v52, s0
	ds_write_b16 v4, v3 offset:63888
	v_cvt_pk_bf16_f32 v3, v53, s0
	ds_write_b16 v5, v3 offset:144
	v_cvt_pk_bf16_f32 v3, v61, s0
	ds_write_b16 v2, v3 offset:144
	v_cvt_pk_bf16_f32 v3, v30, s0
	ds_write_b16 v4, v3 offset:54816
	v_cvt_pk_bf16_f32 v3, v54, s0
	ds_write_b16 v4, v3 offset:64032
	v_cvt_pk_bf16_f32 v3, v55, s0
	ds_write_b16 v5, v3 offset:288
	v_cvt_pk_bf16_f32 v3, v62, s0
	ds_write_b16 v2, v3 offset:288
	v_cvt_pk_bf16_f32 v3, v31, s0
	ds_write_b16 v4, v3 offset:54960
	v_cvt_pk_bf16_f32 v3, v56, s0
	ds_write_b16 v4, v3 offset:64176
	v_cvt_pk_bf16_f32 v3, v57, s0
	ds_write_b16 v5, v3 offset:432
	v_cvt_pk_bf16_f32 v3, v63, s0
	ds_write_b16 v2, v3 offset:432
	v_cvt_pk_bf16_f32 v3, v20, s0
	ds_write_b16 v4, v3 offset:55104
	v_cvt_pk_bf16_f32 v3, v46, s0
	ds_write_b16 v4, v3 offset:64320
	v_cvt_pk_bf16_f32 v3, v50, s0
	ds_write_b16 v5, v3 offset:576
	v_cvt_pk_bf16_f32 v3, v64, s0
	ds_write_b16 v2, v3 offset:576
	v_cvt_pk_bf16_f32 v3, v21, s0
	ds_write_b16 v4, v3 offset:55248
	v_cvt_pk_bf16_f32 v3, v70, s0
	ds_write_b16 v4, v3 offset:64464
	v_cvt_pk_bf16_f32 v3, v58, s0
	ds_write_b16 v5, v3 offset:720
	v_cvt_pk_bf16_f32 v3, v65, s0
	ds_write_b16 v2, v3 offset:720
	v_cvt_pk_bf16_f32 v3, v14, s0
	ds_write_b16 v4, v3 offset:55392
	v_cvt_pk_bf16_f32 v3, v47, s0
	ds_write_b16 v4, v3 offset:64608
	v_cvt_pk_bf16_f32 v3, v51, s0
	ds_write_b16 v5, v3 offset:864
	v_cvt_pk_bf16_f32 v3, v66, s0
	ds_write_b16 v2, v3 offset:864
	v_cvt_pk_bf16_f32 v3, v15, s0
	ds_write_b16 v4, v3 offset:55536
	v_cvt_pk_bf16_f32 v3, v41, s0
	ds_write_b16 v4, v3 offset:64752
	v_cvt_pk_bf16_f32 v3, v43, s0
	ds_write_b16 v5, v3 offset:1008
	v_cvt_pk_bf16_f32 v3, v67, s0
	ds_write_b16 v2, v3 offset:1008
	v_lshrrev_b32_e32 v2, 1, v39
	v_and_b32_e32 v2, 24, v2
	v_or_b32_e32 v21, s57, v59
	v_mul_u32_u24_e32 v44, 0x90, v21
	v_lshlrev_b32_e32 v41, 1, v2
	v_mul_u32_u24_e32 v14, 0x90, v59
	v_add3_u32 v2, s79, v44, v41
	v_add3_u32 v24, s75, v14, v41
	s_waitcnt lgkmcnt(0)
	s_barrier
	ds_read_b128 v[6:9], v2
	ds_read_b128 v[2:5], v2 offset:64
	ds_read_b128 v[10:13], v24
	ds_read_b128 v[26:29], v24 offset:64
	s_waitcnt lgkmcnt(1)
	v_mfma_f32_16x16x32_bf16 v[10:13], v[6:9], v[10:13], 0
	v_bfe_u32 v16, v39, 4, 2
	v_lshlrev_b32_e32 v53, 2, v16
	v_or_b32_e32 v54, s57, v53
	s_waitcnt lgkmcnt(0)
	v_mfma_f32_16x16x32_bf16 v[10:13], v[2:5], v[26:29], v[10:13]
	v_cmp_le_u32_e32 vcc, v59, v54
	v_lshl_add_u32 v23, v59, 1, s78
	s_xor_b64 vcc, s[36:37], vcc
	v_mad_u32_u24 v22, v54, s90, v23
	s_nop 3
	v_cndmask_b32_e32 v10, 0, v10, vcc
	s_and_b64 vcc, exec, s[50:51]
	s_cbranch_vccz .LBB0_1080
	v_cvt_pk_bf16_f32 v15, v10, s0
	ds_write_b16 v22, v15
	s_mov_b64 s[18:19], 0

; #define GAS __attribute__((address_space(1)))
; DI unsigned char* lw(unsigned char* p) { unsigned long long w = (unsigned long long)p; asm volatile("" : "+s"(w)); return (unsigned char*)w; }
; #define LD8(dst, OFF) { unpack8(*(const GAS u32x4*)((const bf16*)(ws + (OFF)) + go), dst); }
; DI void u_rwkv_r1(Frame& F, int c, int h) {
;     ...
;     const int t = tid >> 3, j0 = (tid & 7) * 8;
;     const size_t go = gb + (size_t)t * 512 + j0;
;     float lw[8];
;     { const f32x4 x0 = *(const GAS f32x4*)((const float*)(ws + WS_DEC) + go), x1 = *(const GAS f32x4*)((const float*)(ws + WS_DEC) + go + 4);
; #pragma unroll
;       for (int i = 0; i < 4; ++i) { lw[i] = x0[i]; lw[4 + i] = x1[i]; }
; #pragma unroll
;       for (int i = 0; i < 8; ++i) CUM[t * 68 + j0 + i] = lw[i]; }
;     ...
;         LD8(av, WS_KKN) LD8(bv, WS_BB) LD8(kv, WS_KP) LD8(rv, WS_R32) LD8(vv, WS_VV)
.LBB0_1629:
	s_lshl_b32 s3, s2, 3
	v_mov_b32_e32 v39, v38
	s_and_b32 s18, s3, 0xffffffc0
	s_ashr_i32 s19, s18, 31
	s_lshl_b32 s3, s2, 6
	v_ashrrev_i32_e32 v36, 3, v39
	s_lshl_b64 s[18:19], s[18:19], 9
	s_and_b32 s3, s3, 0x1c0
	v_ashrrev_i32_e32 v37, 31, v36
	s_or_b32 s18, s18, s3
	v_lshlrev_b32_e32 v12, 3, v39
	v_lshlrev_b64 v[2:3], 9, v[36:37]
	v_and_b32_e32 v18, 56, v12
	v_lshl_add_u64 v[10:11], s[18:19], 0, v[2:3]
	v_or_b32_e32 v10, v10, v18
	v_lshl_add_u64 v[2:3], v[10:11], 2, s[8:9]
	global_load_dwordx4 v[6:9], v[2:3], off
	s_nop 0
	global_load_dwordx4 v[2:5], v[2:3], off offset:16
	v_lshlrev_b64 v[54:55], 1, v[10:11]
	v_lshl_add_u64 v[56:57], s[46:47], 0, v[54:55]
	global_load_dwordx4 v[32:35], v[56:57], off
	v_lshl_add_u64 v[56:57], s[16:17], 0, v[54:55]
	global_load_dwordx4 v[40:43], v[56:57], off
	v_lshl_add_u64 v[56:57], s[26:27], 0, v[54:55]
	global_load_dwordx4 v[44:47], v[56:57], off
	v_lshl_add_u64 v[56:57], s[42:43], 0, v[54:55]
	global_load_dwordx4 v[48:51], v[56:57], off
	v_lshl_add_u64 v[56:57], s[44:45], 0, v[54:55]
	global_load_dwordx4 v[66:69], v[56:57], off
	v_mul_lo_u32 v13, v36, s94
	v_lshlrev_b32_e32 v14, 2, v18
	v_add3_u32 v13, s11, v13, v14
	v_cmp_gt_i32_e32 vcc, 64, v39
	s_waitcnt vmcnt(5)
	ds_write2_b32 v13, v6, v7 offset1:1
	ds_write2_b32 v13, v8, v9 offset0:2 offset1:3
	ds_write2_b32 v13, v2, v3 offset0:4 offset1:5
	ds_write2_b32 v13, v4, v5 offset0:6 offset1:7
	s_waitcnt lgkmcnt(0)
	s_barrier
	s_and_saveexec_b64 s[18:19], vcc
	s_cbranch_execz .LBB0_1632
	v_lshl_add_u32 v14, v39, 2, s11
	v_mov_b32_e32 v15, 0
	s_mov_b32 s3, 0

; DI float fexp_(float x) { return __builtin_amdgcn_exp2f(x * 1.4426950408889634f); }
; DI unsigned char* lw(unsigned char* p) { unsigned long long w = (unsigned long long)p; asm volatile("" : "+s"(w)); return (unsigned char*)w; }
; #define LD8(dst, OFF) { unpack8(*(const GAS u32x4*)((const bf16*)(ws + (OFF)) + go), dst); }
; DI void u_rwkv_r1(Frame& F, int c, int h) {
;     ...
;         float cum[8], cT[8];
; #pragma unroll
;         for (int i = 0; i < 8; ++i) { cum[i] = CUM[t * 68 + j0 + i]; cT[i] = CUM[63 * 68 + j0 + i]; }
;         if (t == 0) {
; #pragma unroll
;             for (int i = 0; i < 8; ++i) PT[j0 + i] = fexp_(cT[i]); }
;         float av[8], bv[8], kv[8], rv[8], vv[8];
;     ...
;         LD8(av, WS_KKN) LD8(bv, WS_BB) LD8(kv, WS_KP) LD8(rv, WS_R32) LD8(vv, WS_VV)
;     ...
;         float at[8], bh[8], kh[8], rt[8], bj[8], kj[8];
; #pragma unroll
;         for (int i = 0; i < 8; ++i) { const float pprev = fexp_(cum[i] - lw[i]), pinv = fexp_(-cum[i]), pt = fexp_(cum[i]), pend = fexp_(cT[i] - cum[i]);
;             at[i] = -av[i] * pprev; bh[i] = bv[i] * pinv; kh[i] = kv[i] * pinv; rt[i] = rv[i] * pt; bj[i] = bv[i] * pend; kj[i] = kv[i] * pend; }
.LBB0_1632:
	s_or_b64 exec, exec, s[18:19]
	v_lshl_add_u32 v16, v18, 2, s11
	v_add_u32_e32 v17, 0x42f0, v16
	v_add_u32_e32 v22, 0x42f8, v16
	v_add_u32_e32 v23, 0x4300, v16
	s_waitcnt lgkmcnt(0)
	s_barrier
	ds_read2_b32 v[28:29], v13 offset1:1
	ds_read2_b32 v[24:25], v13 offset0:2 offset1:3
	ds_read2_b32 v[20:21], v13 offset0:4 offset1:5
	ds_read2_b32 v[14:15], v13 offset0:6 offset1:7
	v_add_u32_e32 v13, 0x4308, v16
	ds_read2_b32 v[30:31], v17 offset1:1
	ds_read2_b32 v[26:27], v22 offset1:1
	ds_read2_b32 v[22:23], v23 offset1:1
	ds_read2_b32 v[16:17], v13 offset1:1
	v_cmp_gt_u32_e32 vcc, 8, v39
	s_and_saveexec_b64 s[18:19], vcc
	s_cbranch_execz .LBB0_1634
	s_waitcnt lgkmcnt(3)
	v_mul_f32_e32 v52, 0x3fb8aa3b, v30
	v_mul_f32_e32 v53, 0x3fb8aa3b, v31
	v_exp_f32_e32 v52, v52
	v_exp_f32_e32 v53, v53
	v_lshl_add_u32 v12, v12, 2, s11
	v_add_u32_e32 v13, 0x4400, v12
	ds_write2_b32 v13, v52, v53 offset1:1
	s_waitcnt lgkmcnt(3)
	v_mul_f32_e32 v13, 0x3fb8aa3b, v26
	v_mul_f32_e32 v53, 0x3fb8aa3b, v27
	v_exp_f32_e32 v13, v13
	v_exp_f32_e32 v53, v53
	v_add_u32_e32 v52, 0x4408, v12
	ds_write2_b32 v52, v13, v53 offset1:1
	s_waitcnt lgkmcnt(3)
	v_mul_f32_e32 v13, 0x3fb8aa3b, v22
	v_mul_f32_e32 v53, 0x3fb8aa3b, v23
	v_exp_f32_e32 v13, v13
	v_exp_f32_e32 v53, v53
	v_add_u32_e32 v52, 0x4410, v12
	v_add_u32_e32 v12, 0x4418, v12
	ds_write2_b32 v52, v13, v53 offset1:1
	s_waitcnt lgkmcnt(3)
	v_mul_f32_e32 v13, 0x3fb8aa3b, v16
	v_mul_f32_e32 v52, 0x3fb8aa3b, v17
	v_exp_f32_e32 v13, v13
	v_exp_f32_e32 v52, v52
	ds_write2_b32 v12, v13, v52 offset1:1
.LBB0_1634:
	s_or_b64 exec, exec, s[18:19]
	s_waitcnt lgkmcnt(6)
	v_mul_f32_e32 v55, 0x3fb8aa3b, v24
	v_mul_f32_e32 v60, 0x3fb8aa3b, v25
	v_sub_f32_e32 v6, v28, v6
	v_mul_f32_e32 v37, 0xbfb8aa3b, v28
	v_mul_f32_e32 v52, 0x3fb8aa3b, v28
	s_waitcnt lgkmcnt(3)
	v_sub_f32_e32 v28, v30, v28
	s_waitcnt lgkmcnt(2)
	v_sub_f32_e32 v56, v26, v24
	v_sub_f32_e32 v61, v27, v25
	v_exp_f32_e32 v26, v55
	v_exp_f32_e32 v27, v60
	v_sub_f32_e32 v7, v29, v7
	v_mul_f32_e32 v30, 0xbfb8aa3b, v29
	v_mul_f32_e32 v53, 0x3fb8aa3b, v29
	v_sub_f32_e32 v29, v31, v29
	v_sub_f32_e32 v31, v24, v8
	v_mul_f32_e32 v54, 0xbfb8aa3b, v24
	v_sub_f32_e32 v57, v25, v9
	v_mul_f32_e32 v62, 0x3fb8aa3b, v6
	v_exp_f32_e32 v6, v37
	v_mul_f32_e32 v37, 0x3fb8aa3b, v28
	v_mul_f32_e32 v58, 0xbfb8aa3b, v25
	v_exp_f32_e32 v8, v52
	v_mul_f32_e32 v52, 0x3fb8aa3b, v7
	v_exp_f32_e32 v7, v30
	v_mul_f32_e32 v30, 0x3fb8aa3b, v29
	v_mul_f32_e32 v31, 0x3fb8aa3b, v31
	v_exp_f32_e32 v24, v54
	v_mul_f32_e32 v54, 0x3fb8aa3b, v57
	v_mul_f32_e32 v55, 0x3fb8aa3b, v61
	v_exp_f32_e32 v37, v37
	v_exp_f32_e32 v9, v53
	v_mul_f32_e32 v53, 0x3fb8aa3b, v56
	v_exp_f32_e32 v25, v58
	v_exp_f32_e32 v56, v30
	v_exp_f32_e32 v30, v31
	v_exp_f32_e32 v31, v54
	v_exp_f32_e32 v58, v55
	v_sub_f32_e32 v2, v20, v2
	v_exp_f32_e32 v29, v52
	v_exp_f32_e32 v28, v62
	v_exp_f32_e32 v57, v53
	v_sub_f32_e32 v3, v21, v3
	v_mul_f32_e32 v2, 0x3fb8aa3b, v2
	v_mul_f32_e32 v3, 0x3fb8aa3b, v3
	v_exp_f32_e32 v2, v2
	v_exp_f32_e32 v3, v3
	v_and_b32_e32 v59, 15, v39
	s_mov_b64 s[18:19], -1
	s_waitcnt vmcnt(4)
	v_lshlrev_b32_e32 v64, 16, v34
	v_and_b32_e32 v65, 0xffff0000, v34
	v_lshlrev_b32_e32 v60, 16, v32
	v_and_b32_e32 v61, 0xffff0000, v32
	s_waitcnt vmcnt(2)
	v_lshlrev_b32_e32 v34, 16, v44
	v_lshlrev_b32_e32 v62, 16, v33
	v_and_b32_e32 v63, 0xffff0000, v33
	s_waitcnt vmcnt(1)
	v_lshlrev_b32_e32 v52, 16, v48
	v_lshlrev_b32_e32 v32, 16, v40
	s_waitcnt vmcnt(0)
	v_mov_b32_e32 v10, v66
	v_mov_b32_e32 v11, v67
	v_mov_b32_e32 v12, v68
	v_mov_b32_e32 v13, v69
	v_lshlrev_b32_e32 v54, 16, v10
	v_and_b32_e32 v55, 0xffff0000, v10
	v_lshlrev_b32_e32 v10, 16, v11
	v_and_b32_e32 v11, 0xffff0000, v11
	v_pk_mul_f32 v[10:11], v[26:27], v[10:11]
	v_mul_f32_e32 v26, 0xbfb8aa3b, v20
	v_mul_f32_e32 v27, 0x3fb8aa3b, v20
	s_waitcnt lgkmcnt(1)
	v_sub_f32_e32 v20, v22, v20
	v_mul_f32_e32 v20, 0x3fb8aa3b, v20
	v_and_b32_e32 v33, 0xffff0000, v40
	v_lshlrev_b32_e32 v40, 16, v41
	v_and_b32_e32 v41, 0xffff0000, v41
	v_mul_f32_e32 v68, v37, v34
	v_mul_f32_e32 v69, v37, v52
	v_exp_f32_e32 v37, v20
	v_mul_f32_e32 v20, 0xbfb8aa3b, v21
	v_pk_mul_f32 v[30:31], v[30:31], v[40:41] neg_lo:[0,1] neg_hi:[0,1]
	v_exp_f32_e32 v40, v27
	v_exp_f32_e32 v27, v20
	v_mul_f32_e32 v20, 0x3fb8aa3b, v21
	v_exp_f32_e32 v41, v20
	v_sub_f32_e32 v20, v23, v21
	v_lshlrev_b32_e32 v66, 16, v35
	v_and_b32_e32 v67, 0xffff0000, v35
	v_and_b32_e32 v35, 0xffff0000, v44
	v_and_b32_e32 v53, 0xffff0000, v48
	v_lshlrev_b32_e32 v44, 16, v45
	v_and_b32_e32 v45, 0xffff0000, v45
	v_lshlrev_b32_e32 v48, 16, v49
	v_and_b32_e32 v49, 0xffff0000, v49
	v_mul_f32_e32 v20, 0x3fb8aa3b, v20
	v_pk_mul_f32 v[28:29], v[28:29], v[32:33] neg_lo:[0,1] neg_hi:[0,1]
	v_pk_mul_f32 v[32:33], v[6:7], v[34:35]
	v_pk_mul_f32 v[6:7], v[6:7], v[52:53]
	v_pk_mul_f32 v[8:9], v[8:9], v[54:55]
	v_mul_f32_e32 v52, v56, v35
	v_mul_f32_e32 v53, v56, v53
	v_mul_f32_e32 v54, v57, v44
	v_mul_f32_e32 v55, v57, v48
	v_mul_f32_e32 v56, v58, v45
	v_mul_f32_e32 v57, v58, v49
	v_exp_f32_e32 v26, v26
	v_exp_f32_e32 v58, v20
	v_lshlrev_b32_e32 v20, 16, v42
	v_and_b32_e32 v21, 0xffff0000, v42
	v_pk_mul_f32 v[20:21], v[2:3], v[20:21] neg_lo:[0,1] neg_hi:[0,1]
	v_lshlrev_b32_e32 v2, 16, v46
	v_and_b32_e32 v3, 0xffff0000, v46
	v_pk_mul_f32 v[22:23], v[26:27], v[2:3]
	v_mul_f32_e32 v70, v58, v3
	v_mul_f32_e32 v3, 0xbfb8aa3b, v14
	v_pk_mul_f32 v[34:35], v[24:25], v[44:45]
	v_pk_mul_f32 v[24:25], v[24:25], v[48:49]
	v_mul_f32_e32 v46, v37, v2
	v_lshlrev_b32_e32 v48, 16, v12
	v_and_b32_e32 v49, 0xffff0000, v12
	v_sub_f32_e32 v2, v14, v4
	v_exp_f32_e32 v4, v3
	v_mul_f32_e32 v3, 0x3fb8aa3b, v14
	v_pk_mul_f32 v[48:49], v[40:41], v[48:49]
	v_exp_f32_e32 v40, v3
	s_waitcnt lgkmcnt(0)
; #define LAS __attribute__((address_space(3)))
; DI unsigned f2bf(float f) { const __bf16 b = (__bf16)f; return (unsigned)__builtin_bit_cast(unsigned short, b); }
; DI float fexp_(float x) { return __builtin_amdgcn_exp2f(x * 1.4426950408889634f); }
; DI unsigned char* lw(unsigned char* p) { unsigned long long w = (unsigned long long)p; asm volatile("" : "+s"(w)); return (unsigned char*)w; }
; #define MFMA16(a, b, c) __builtin_amdgcn_mfma_f32_16x16x32_bf16((a), (b), (c), 0, 0, 0)
; #define ST8(M, v) { u32x4 o; o.x = pk2(v[0], v[1]); o.y = pk2(v[2], v[3]); o.z = pk2(v[4], v[5]); o.w = pk2(v[6], v[7]); *(LAS u32x4*)(M + t * 72 + j0) = o; }
; DI void u_rwkv_r1(Frame& F, int c, int h) {
;     ...
;         float at[8], bh[8], kh[8], rt[8], bj[8], kj[8];
; #pragma unroll
;         for (int i = 0; i < 8; ++i) { const float pprev = fexp_(cum[i] - lw[i]), pinv = fexp_(-cum[i]), pt = fexp_(cum[i]), pend = fexp_(cT[i] - cum[i]);
;             at[i] = -av[i] * pprev; bh[i] = bv[i] * pinv; kh[i] = kv[i] * pinv; rt[i] = rv[i] * pt; bj[i] = bv[i] * pend; kj[i] = kv[i] * pend; }
;     ...
;         ST8(AT, at) ST8(BH, bh) ST8(KH, kh) ST8(RT, rt)
;     ...
; #pragma unroll
;         for (int i = 0; i < 8; ++i) { const int o = (j0 + i) * 72 + t; AJ[o] = (bf16)f2bf(at[i]); BJ[o] = (bf16)f2bf(bj[i]); KJ[o] = (bf16)f2bf(kj[i]); VJ[o] = (bf16)f2bf(vv[i]); }
;     }
;     __syncthreads();
;     {
;         const int q = w >> 1; const LAS bf16* Am = (q == 0) ? BH : (q == 1) ? KH : RT; const LAS bf16* Bm = (q < 2) ? AT : (q == 2) ? BH : KH;
; #pragma unroll
;         for (int bi = 0; bi < 2; ++bi) { const int bm = 2 * (w & 1) + bi; const bf16x8 a0 = ldfrag(Am, 72, 16 * bm, 0, lane), a1 = ldfrag(Am, 72, 16 * bm, 32, lane);
; #pragma unroll
;             for (int bn = 0; bn < 4; ++bn) { f32x4 acc = (f32x4){0.f, 0.f, 0.f, 0.f};
;                 acc = MFMA16(a0, ldfrag(Bm, 72, 16 * bn, 0, lane), acc); acc = MFMA16(a1, ldfrag(Bm, 72, 16 * bn, 32, lane), acc);
; #pragma unroll
;                 for (int r = 0; r < 4; ++r) { const int row = 16 * bm + 4 * g4 + r, col = 16 * bn + lc; const bool keep = (q < 2) ? (row < col) : (col <= row); const float v = keep ? acc[r] : 0.f;
;                     if (q == 0) CUM[row * 68 + col] = v; else { LAS bf16* O = (q == 1) ? MAK : (q == 2) ? MRBT : MRKT; O[row * 72 + col] = (bf16)f2bf(v); } } } }
	v_sub_f32_e32 v3, v16, v14
	v_mul_f32_e32 v3, 0x3fb8aa3b, v3
	v_exp_f32_e32 v12, v3
	v_sub_f32_e32 v3, v15, v5
	v_mul_f32_e32 v2, 0x3fb8aa3b, v2
	v_mul_f32_e32 v3, 0x3fb8aa3b, v3
	v_mul_f32_e32 v14, 0x3fb8aa3b, v15
	v_exp_f32_e32 v2, v2
	v_exp_f32_e32 v3, v3
	v_mul_f32_e32 v5, 0xbfb8aa3b, v15
	v_exp_f32_e32 v41, v14
	v_sub_f32_e32 v14, v17, v15
	v_lshlrev_b32_e32 v44, 16, v50
	v_exp_f32_e32 v5, v5
	v_mul_f32_e32 v14, 0x3fb8aa3b, v14
	v_and_b32_e32 v45, 0xffff0000, v50
	v_mul_f32_e32 v50, v37, v44
	v_exp_f32_e32 v37, v14
	v_lshlrev_b32_e32 v14, 16, v43
	v_and_b32_e32 v15, 0xffff0000, v43
	v_pk_mul_f32 v[14:15], v[2:3], v[14:15] neg_lo:[0,1] neg_hi:[0,1]
	v_lshlrev_b32_e32 v2, 16, v47
	v_and_b32_e32 v3, 0xffff0000, v47
	v_lshlrev_b32_e32 v42, 16, v51
	v_and_b32_e32 v43, 0xffff0000, v51
	v_pk_mul_f32 v[26:27], v[26:27], v[44:45]
	v_mul_f32_e32 v58, v58, v45
	v_pk_mul_f32 v[16:17], v[4:5], v[2:3]
	v_pk_mul_f32 v[44:45], v[4:5], v[42:43]
	v_lshlrev_b32_e32 v4, 16, v13
	v_and_b32_e32 v5, 0xffff0000, v13
	v_mul_f32_e32 v47, v12, v2
	v_mul_f32_e32 v51, v12, v42
	v_pk_mul_f32 v[12:13], v[40:41], v[4:5]
	v_mul_f32_e32 v41, v37, v3
	v_mul_f32_e32 v43, v37, v43
	v_mul_lo_u32 v37, v36, s95
	v_lshlrev_b32_e32 v37, 1, v37
	v_lshlrev_b32_e32 v40, 1, v18
	v_cvt_pk_bf16_f32 v2, v28, v29
	v_cvt_pk_bf16_f32 v3, v30, v31
	v_cvt_pk_bf16_f32 v4, v20, v21
	v_cvt_pk_bf16_f32 v5, v14, v15
	v_add3_u32 v42, s11, v37, v40
	ds_write_b128 v42, v[2:5] offset:17664
	v_cvt_pk_bf16_f32 v2, v32, v33
	v_cvt_pk_bf16_f32 v3, v34, v35
	v_cvt_pk_bf16_f32 v4, v22, v23
	v_cvt_pk_bf16_f32 v5, v16, v17
	ds_write_b128 v42, v[2:5] offset:26880
	v_cvt_pk_bf16_f32 v2, v6, v7
	v_cvt_pk_bf16_f32 v3, v24, v25
	v_cvt_pk_bf16_f32 v4, v26, v27
	v_cvt_pk_bf16_f32 v5, v44, v45
	ds_write_b128 v42, v[2:5] offset:36096
	v_cvt_pk_bf16_f32 v2, v8, v9
	v_cvt_pk_bf16_f32 v3, v10, v11
	v_cvt_pk_bf16_f32 v4, v48, v49
	v_cvt_pk_bf16_f32 v5, v12, v13
	ds_write_b128 v42, v[2:5] offset:45312
	v_mul_u32_u24_e32 v2, 0x48, v18
	v_add_lshl_u32 v2, v2, v36, 1
	v_cvt_pk_bf16_f32 v3, v28, s0
	v_add_u32_e32 v4, s11, v2
	ds_write_b16 v4, v3 offset:54528
	v_cvt_pk_bf16_f32 v3, v68, s0
	ds_write_b16 v4, v3 offset:63744
	v_cvt_pk_bf16_f32 v3, v69, s0
	v_add_u32_e32 v5, s53, v2
	ds_write_b16 v5, v3
	v_cvt_pk_bf16_f32 v3, v60, s0
	v_add_u32_e32 v2, s20, v2
	ds_write_b16 v2, v3
	v_cvt_pk_bf16_f32 v3, v29, s0
	ds_write_b16 v4, v3 offset:54672
	v_cvt_pk_bf16_f32 v3, v52, s0
	ds_write_b16 v4, v3 offset:63888
	v_cvt_pk_bf16_f32 v3, v53, s0
	ds_write_b16 v5, v3 offset:144
	v_cvt_pk_bf16_f32 v3, v61, s0
	ds_write_b16 v2, v3 offset:144
	v_cvt_pk_bf16_f32 v3, v30, s0
	ds_write_b16 v4, v3 offset:54816
	v_cvt_pk_bf16_f32 v3, v54, s0
	ds_write_b16 v4, v3 offset:64032
	v_cvt_pk_bf16_f32 v3, v55, s0
	ds_write_b16 v5, v3 offset:288
	v_cvt_pk_bf16_f32 v3, v62, s0
	ds_write_b16 v2, v3 offset:288
	v_cvt_pk_bf16_f32 v3, v31, s0
	ds_write_b16 v4, v3 offset:54960
	v_cvt_pk_bf16_f32 v3, v56, s0
	ds_write_b16 v4, v3 offset:64176
	v_cvt_pk_bf16_f32 v3, v57, s0
	ds_write_b16 v5, v3 offset:432
	v_cvt_pk_bf16_f32 v3, v63, s0
	ds_write_b16 v2, v3 offset:432
	v_cvt_pk_bf16_f32 v3, v20, s0
	ds_write_b16 v4, v3 offset:55104
	v_cvt_pk_bf16_f32 v3, v46, s0
	ds_write_b16 v4, v3 offset:64320
	v_cvt_pk_bf16_f32 v3, v50, s0
	ds_write_b16 v5, v3 offset:576
	v_cvt_pk_bf16_f32 v3, v64, s0
	ds_write_b16 v2, v3 offset:576
	v_cvt_pk_bf16_f32 v3, v21, s0
	ds_write_b16 v4, v3 offset:55248
	v_cvt_pk_bf16_f32 v3, v70, s0
	ds_write_b16 v4, v3 offset:64464
	v_cvt_pk_bf16_f32 v3, v58, s0
	ds_write_b16 v5, v3 offset:720
	v_cvt_pk_bf16_f32 v3, v65, s0
	ds_write_b16 v2, v3 offset:720
	v_cvt_pk_bf16_f32 v3, v14, s0
	ds_write_b16 v4, v3 offset:55392
	v_cvt_pk_bf16_f32 v3, v47, s0
	ds_write_b16 v4, v3 offset:64608
	v_cvt_pk_bf16_f32 v3, v51, s0
	ds_write_b16 v5, v3 offset:864
	v_cvt_pk_bf16_f32 v3, v66, s0
	ds_write_b16 v2, v3 offset:864
	v_cvt_pk_bf16_f32 v3, v15, s0
	ds_write_b16 v4, v3 offset:55536
	v_cvt_pk_bf16_f32 v3, v41, s0
	ds_write_b16 v4, v3 offset:64752
	v_cvt_pk_bf16_f32 v3, v43, s0
	ds_write_b16 v5, v3 offset:1008
	v_cvt_pk_bf16_f32 v3, v67, s0
	ds_write_b16 v2, v3 offset:1008
	v_lshrrev_b32_e32 v2, 1, v39
	v_and_b32_e32 v2, 24, v2
	v_or_b32_e32 v21, s56, v59
	v_mul_u32_u24_e32 v44, 0x90, v21
	v_lshlrev_b32_e32 v41, 1, v2
	v_mul_u32_u24_e32 v14, 0x90, v59
	v_add3_u32 v2, s76, v44, v41
	v_add3_u32 v24, s72, v14, v41
	s_waitcnt lgkmcnt(0)
	s_barrier
	ds_read_b128 v[6:9], v2
	ds_read_b128 v[2:5], v2 offset:64
	ds_read_b128 v[10:13], v24
	ds_read_b128 v[26:29], v24 offset:64
	s_waitcnt lgkmcnt(1)
	v_mfma_f32_16x16x32_bf16 v[10:13], v[6:9], v[10:13], 0
	v_bfe_u32 v16, v39, 4, 2
	v_lshlrev_b32_e32 v53, 2, v16
	v_or_b32_e32 v54, s56, v53
	s_waitcnt lgkmcnt(0)
	v_mfma_f32_16x16x32_bf16 v[10:13], v[2:5], v[26:29], v[10:13]
	v_cmp_le_u32_e32 vcc, v59, v54
	v_lshl_add_u32 v23, v59, 1, s75
	s_xor_b64 vcc, s[36:37], vcc
	v_mad_u32_u24 v22, v54, s90, v23
	s_nop 3
	v_cndmask_b32_e32 v10, 0, v10, vcc
	s_and_b64 vcc, exec, s[48:49]
	s_cbranch_vccz .LBB0_1636
	v_cvt_pk_bf16_f32 v15, v10, s0
	ds_write_b16 v22, v15
	s_mov_b64 s[18:19], 0
